# scan prefetch (roles 2/3): interior chunks take an unmasked fast path (no zero-init, no exec masks, one 64-bit add per neighbour row); masked code kept out of line for the last chunk
# baseline (speedup 1.0000x reference)
; __device__ __forceinline__ void load_raw16(Raw16& r, const bf16_t* __restrict__ z, int row, int t, int T, int col) {
;   const bf16_t* pz = z + (unsigned)(row * ZLD + col);
;   r.c0 = *(const uint4*)pz; r.c1 = *(const uint4*)(pz + 8);
;   r.p0 = make_uint4(0, 0, 0, 0); r.p1 = r.p0; r.n0 = r.p0; r.n1 = r.p0;
;   if (t > 0) { r.p0 = *(const uint4*)(pz - ZLD); r.p1 = *(const uint4*)(pz - ZLD + 8); }
;   if (t < T - 1) { r.n0 = *(const uint4*)(pz + ZLD); r.n1 = *(const uint4*)(pz + ZLD + 8); }
; __device__ __forceinline__ void scan_phase(PREF p, char* smem, const int wid_u) {
;     ...
;       if (c + 2 < nch) {
;         const int is2 = (c + 2) * 32 + th * 16 + tl;
;         const int t2 = d ? T - 1 - is2 : is2;
;         const int row2 = r0seq + t2;
;         if (role >= 2) load_raw16(ra, z, row2, t2, T, colA);
;         if (role == 3) load_raw16(rb, z, row2, t2, T, colB);
.LBB0_592:
	v_mad_u64_u32 v[0:1], s[82:83], v59, s88, v[74:75]
	v_mov_b32_e32 v1, v79
	v_lshl_add_u64 v[56:57], v[0:1], 1, s[50:51]
	global_load_dwordx4 v[16:19], v[56:57], off offset:16
	global_load_dwordx4 v[12:15], v[56:57], off
	s_add_i32 s99, s94, 1
	s_cmp_eq_u32 s99, s44
	s_cbranch_scc1 .Lpf_slow_a
	v_lshl_add_u64 v[8:9], v[56:57], 0, s[76:77]
	v_lshl_add_u64 v[28:29], v[56:57], 0, s[78:79]
	global_load_dwordx4 v[4:7], v[8:9], off
	s_nop 0
	global_load_dwordx4 v[8:11], v[8:9], off offset:16
	global_load_dwordx4 v[0:3], v[28:29], off
	s_nop 0
	global_load_dwordx4 v[28:31], v[28:29], off offset:16

; __device__ __forceinline__ void load_raw16(Raw16& r, const bf16_t* __restrict__ z, int row, int t, int T, int col) {
;   const bf16_t* pz = z + (unsigned)(row * ZLD + col);
;   r.c0 = *(const uint4*)pz; r.c1 = *(const uint4*)(pz + 8);
;   r.p0 = make_uint4(0, 0, 0, 0); r.p1 = r.p0; r.n0 = r.p0; r.n1 = r.p0;
;   if (t > 0) { r.p0 = *(const uint4*)(pz - ZLD); r.p1 = *(const uint4*)(pz - ZLD + 8); }
;   if (t < T - 1) { r.n0 = *(const uint4*)(pz + ZLD); r.n1 = *(const uint4*)(pz + ZLD + 8); }
; __device__ __forceinline__ void scan_phase(PREF p, char* smem, const int wid_u) {
;     ...
;       if (c + 2 < nch) {
;         const int is2 = (c + 2) * 32 + th * 16 + tl;
;         const int t2 = d ? T - 1 - is2 : is2;
;         const int row2 = r0seq + t2;
;         if (role >= 2) load_raw16(ra, z, row2, t2, T, colA);
;         if (role == 3) load_raw16(rb, z, row2, t2, T, colB);
.LBB0_597:
	v_mad_u64_u32 v[20:21], s[40:41], v59, s88, v[76:77]
	v_mov_b32_e32 v21, v79
	v_lshl_add_u64 v[56:57], v[20:21], 1, s[50:51]
	global_load_dwordx4 v[20:23], v[56:57], off offset:16
	global_load_dwordx4 v[24:27], v[56:57], off
	s_add_i32 s99, s94, 1
	s_cmp_eq_u32 s99, s44
	s_cbranch_scc1 .Lpf_slow_b
	v_lshl_add_u64 v[40:41], v[56:57], 0, s[76:77]
	v_lshl_add_u64 v[44:45], v[56:57], 0, s[78:79]
	global_load_dwordx4 v[36:39], v[40:41], off
	s_nop 0
	global_load_dwordx4 v[40:43], v[40:41], off offset:16
	global_load_dwordx4 v[32:35], v[44:45], off
	s_nop 0
	global_load_dwordx4 v[44:47], v[44:45], off offset:16
.Lpf_join_b:
	s_and_b64 vcc, exec, s[4:5]
	s_cbranch_vccz .LBB0_586
	s_branch .LBB0_587

; __device__ __forceinline__ void load_raw16(Raw16& r, const bf16_t* __restrict__ z, int row, int t, int T, int col) {
;   const bf16_t* pz = z + (unsigned)(row * ZLD + col);
;   r.c0 = *(const uint4*)pz; r.c1 = *(const uint4*)(pz + 8);
;   r.p0 = make_uint4(0, 0, 0, 0); r.p1 = r.p0; r.n0 = r.p0; r.n1 = r.p0;
;   if (t > 0) { r.p0 = *(const uint4*)(pz - ZLD); r.p1 = *(const uint4*)(pz - ZLD + 8); }
;   if (t < T - 1) { r.n0 = *(const uint4*)(pz + ZLD); r.n1 = *(const uint4*)(pz + ZLD + 8); }
.Lpf_slow_a:
	v_mov_b32_e32 v2, v79
	v_mov_b32_e32 v3, v79
	v_mov_b32_e32 v0, 0
	v_mov_b64_e32 v[10:11], v[2:3]
	v_mov_b64_e32 v[6:7], v[2:3]
	v_mov_b64_e32 v[8:9], v[0:1]
	v_mov_b64_e32 v[4:5], v[0:1]
	s_and_saveexec_b64 s[82:83], s[40:41]
	s_cbranch_execz .LBB0_594
	v_add_co_u32_e32 v4, vcc, 0xfffff000, v56
	v_lshl_add_u64 v[8:9], v[56:57], 0, s[76:77]
	s_nop 0
	v_addc_co_u32_e32 v5, vcc, -1, v57, vcc
	global_load_dwordx4 v[4:7], v[4:5], off offset:-1024
	s_nop 0
	global_load_dwordx4 v[8:11], v[8:9], off offset:16

; __device__ __forceinline__ void load_raw16(Raw16& r, const bf16_t* __restrict__ z, int row, int t, int T, int col) {
;   const bf16_t* pz = z + (unsigned)(row * ZLD + col);
;   r.c0 = *(const uint4*)pz; r.c1 = *(const uint4*)(pz + 8);
;   r.p0 = make_uint4(0, 0, 0, 0); r.p1 = r.p0; r.n0 = r.p0; r.n1 = r.p0;
;   if (t > 0) { r.p0 = *(const uint4*)(pz - ZLD); r.p1 = *(const uint4*)(pz - ZLD + 8); }
;   if (t < T - 1) { r.n0 = *(const uint4*)(pz + ZLD); r.n1 = *(const uint4*)(pz + ZLD + 8); }
; __device__ __forceinline__ void scan_phase(PREF p, char* smem, const int wid_u) {
;     ...
;         if (role >= 2) load_raw16(ra, z, row2, t2, T, colA);
;         if (role == 3) load_raw16(rb, z, row2, t2, T, colB);
.LBB0_596:
	s_or_b64 exec, exec, s[40:41]
	s_branch .Lpf_join_a
.Lpf_slow_b:
	v_mov_b32_e32 v34, v79
	v_mov_b32_e32 v35, v79
	v_mov_b32_e32 v32, 0
	v_mov_b32_e32 v33, v79
	v_mov_b64_e32 v[42:43], v[34:35]
	v_mov_b64_e32 v[38:39], v[34:35]
	v_cmp_lt_i32_e32 vcc, 0, v58
	v_mov_b64_e32 v[40:41], v[32:33]
	v_mov_b64_e32 v[36:37], v[32:33]
	s_and_saveexec_b64 s[40:41], vcc
	s_cbranch_execz .LBB0_599
	v_add_co_u32_e32 v36, vcc, 0xfffff000, v56
	v_lshl_add_u64 v[40:41], v[56:57], 0, s[76:77]
	s_nop 0
	v_addc_co_u32_e32 v37, vcc, -1, v57, vcc
	global_load_dwordx4 v[36:39], v[36:37], off offset:-1024
	s_nop 0
	global_load_dwordx4 v[40:43], v[40:41], off offset:16
